# gate-up GEMM: cross-tile prefetch, the next tile's first K-tile is DMA'd into the free LDS stage during the last K-phase (pieces interleaved with the MFMAs); next prologue issues no DMA and leaves the
# speedup vs baseline: 1.0021x; 1.0021x over previous
.LBB0_59:
	s_movk_i32 s2, 0x13ff
	v_and_b32_e32 v0, 7, v134
	v_cmp_lt_i32_e32 vcc, s2, v134
	s_and_saveexec_b64 s[2:3], vcc
	s_xor_b64 s[2:3], exec, s[2:3]
	v_add_u32_e32 v2, 0xffffec00, v134
	v_bfe_u32 v3, v134, 3, 4
	v_lshl_or_b32 v135, v0, 4, v3
	v_lshrrev_b32_e32 v0, 7, v2
	v_add_u32_e32 v136, 40, v0
	s_andn2_saveexec_b64 s[2:3], s[2:3]
	v_lshrrev_b32_e32 v3, 6, v134
	v_bfe_u32 v2, v134, 3, 3
	v_lshlrev_b32_e32 v0, 4, v0
	v_and_b32_e32 v4, 8, v3
	v_or3_b32 v135, v0, v4, v2
	v_ashrrev_i32_e32 v0, 7, v134
	v_bfi_b32 v136, -8, v0, v3
	s_or_b64 exec, exec, s[2:3]
	v_mov_b64_e32 v[2:3], s[80:81]
	s_mov_b32 s4, 0x44000
	v_mad_u64_u32 v[4:5], s[2:3], v135, s4, v[2:3]
	v_mov_b64_e32 v[2:3], s[56:57]
	v_mad_i64_i32 v[6:7], s[2:3], v136, s4, v[2:3]
	v_mov_b32_e32 v2, v163
	s_mov_b32 s4, 0x22000
	v_ashrrev_i32_e32 v3, 3, v2
	v_lshlrev_b32_e32 v0, 4, v2
	v_mad_i64_i32 v[4:5], s[2:3], v3, s43, v[4:5]
	v_and_b32_e32 v0, 0x70, v0
	v_lshl_add_u64 v[130:131], v[4:5], 0, v[0:1]
	v_mad_i64_i32 v[4:5], s[2:3], v3, s43, v[6:7]
	v_lshl_add_u64 v[132:133], v[4:5], 0, v[0:1]
	v_and_b32_e32 v110, 7, v163
	v_bfe_u32 v111, v163, 4, 3
	v_xor_b32_e32 v111, v111, v110
	v_sub_u32_e32 v111, v111, v110
	v_lshlrev_b32_e32 v111, 4, v111
	v_lshrrev_b32_e32 v112, 6, v163
	v_lshlrev_b32_e32 v112, 10, v112
	v_readfirstlane_b32 s2, v130
	v_readfirstlane_b32 s3, v131
	v_readfirstlane_b32 s4, v132
	v_readfirstlane_b32 s5, v133
	v_readfirstlane_b32 s6, v112
	s_nop 3
	v_subrev_u32_e32 v98, s2, v130
	v_subrev_u32_e32 v102, s4, v132
	v_add_u32_e32 v98, v98, v111
	v_add_u32_e32 v102, v102, v111
	v_add_u32_e32 v99, 0x11000, v98
	v_add_u32_e32 v103, 0x11000, v102
	v_add_u32_e32 v100, 0x22000, v98
	v_add_u32_e32 v104, 0x22000, v102
	v_add_u32_e32 v101, 0x33000, v98
	v_add_u32_e32 v105, 0x33000, v102
	v_lshlrev_b32_e32 v110, 3, v163
	v_lshlrev_b32_e32 v111, 7, v163
	v_and_b32_e32 v112, 0x2000, v111
	v_and_b32_e32 v111, 0x780, v111
	v_and_b32_e32 v107, 64, v110
	v_xor_b32_e32 v110, v110, v163
	v_and_b32_e32 v110, 48, v110
	v_or3_b32 v110, v111, v107, v110
	v_lshlrev_b32_e32 v111, 6, v163
	v_and_b32_e32 v111, 0xffffe000, v111
	v_or_b32_e32 v108, v110, v112
	v_or_b32_e32 v106, v110, v111
	v_xor_b32_e32 v107, 64, v106
	v_xor_b32_e32 v109, 64, v108
	v_readlane_b32 s9, v234, 23
	s_cmp_eq_u32 s9, 1
	s_cbranch_scc1 .Lg9_have0
	s_add_u32 m0, s6, 0x8000
	s_nop 0
	global_load_lds_dwordx4 v98, s[2:3]
	s_add_u32 m0, s6, 0x9000
	s_nop 0
	global_load_lds_dwordx4 v99, s[2:3]
	s_add_u32 m0, s6, 0xa000
	s_nop 0
	global_load_lds_dwordx4 v100, s[2:3]
	s_add_u32 m0, s6, 0xb000
	s_nop 0
	global_load_lds_dwordx4 v101, s[2:3]
	s_add_u32 m0, s6, 0xc000
	s_nop 0
	global_load_lds_dwordx4 v102, s[4:5]
	s_add_u32 m0, s6, 0xd000
	s_nop 0
	global_load_lds_dwordx4 v103, s[4:5]
	s_add_u32 m0, s6, 0xe000
	s_nop 0
	global_load_lds_dwordx4 v104, s[4:5]
	s_add_u32 m0, s6, 0xf000
	s_nop 0
	global_load_lds_dwordx4 v105, s[4:5]
	s_waitcnt vmcnt(0)
	s_branch .Lg9_go
.Lg9_have0:
	v_writelane_b32 v234, s41, 23
	s_waitcnt vmcnt(4)
.Lg9_go:
	s_add_u32 s2, s2, 0x80
	s_addc_u32 s3, s3, 0
	s_add_u32 s4, s4, 0x80
	s_addc_u32 s5, s5, 0
	s_barrier
	s_mov_b32 m0, s6
	ds_read_b128 v[142:145], v106 offset:32768
	ds_read_b128 v[158:161], v108 offset:49152
	s_nop 0
	global_load_lds_dwordx4 v98, s[2:3]
	s_add_u32 m0, s6, 0x1000
	ds_read_b128 v[182:185], v108 offset:51200
	ds_read_b128 v[186:189], v108 offset:53248
	s_nop 0
	global_load_lds_dwordx4 v99, s[2:3]
	s_add_u32 m0, s6, 0x2000
	ds_read_b128 v[206:209], v108 offset:55296
	ds_read_b128 v[146:149], v106 offset:34816
	s_nop 0
	global_load_lds_dwordx4 v100, s[2:3]
	s_add_u32 m0, s6, 0x3000
	ds_read_b128 v[150:153], v106 offset:36864
	ds_read_b128 v[154:157], v106 offset:38912
	s_nop 0
	global_load_lds_dwordx4 v101, s[2:3]
	s_add_u32 m0, s6, 0x4000
	s_nop 0
	global_load_lds_dwordx4 v102, s[4:5]
	s_add_u32 m0, s6, 0x5000
	s_nop 0
	global_load_lds_dwordx4 v103, s[4:5]
	s_add_u32 m0, s6, 0x6000
	s_nop 0
	global_load_lds_dwordx4 v104, s[4:5]
	s_add_u32 m0, s6, 0x7000
	s_nop 0
	global_load_lds_dwordx4 v105, s[4:5]
	s_add_u32 s2, s2, 0x80
	s_addc_u32 s3, s3, 0
	s_add_u32 s4, s4, 0x80
	s_addc_u32 s5, s5, 0
	s_waitcnt lgkmcnt(0)
	v_mfma_f32_16x16x32_bf16 v[90:93], v[158:161], v[142:145], 0
	ds_read_b128 v[58:61], v107 offset:32768
	ds_read_b128 v[74:77], v109 offset:49152
	v_mfma_f32_16x16x32_bf16 v[54:57], v[182:185], v[142:145], 0
	v_mfma_f32_16x16x32_bf16 v[86:89], v[186:189], v[142:145], 0
	ds_read_b128 v[78:81], v109 offset:51200
	ds_read_b128 v[82:85], v109 offset:53248
	v_mfma_f32_16x16x32_bf16 v[50:53], v[206:209], v[142:145], 0
	v_mfma_f32_16x16x32_bf16 v[46:49], v[158:161], v[146:149], 0
	ds_read_b128 v[94:97], v109 offset:55296
	ds_read_b128 v[62:65], v107 offset:34816
	v_mfma_f32_16x16x32_bf16 v[38:41], v[182:185], v[146:149], 0
	v_mfma_f32_16x16x32_bf16 v[42:45], v[186:189], v[146:149], 0
	ds_read_b128 v[66:69], v107 offset:36864
	ds_read_b128 v[70:73], v107 offset:38912
	v_mfma_f32_16x16x32_bf16 v[34:37], v[206:209], v[146:149], 0
	v_mfma_f32_16x16x32_bf16 v[30:33], v[158:161], v[150:153], 0
	v_mfma_f32_16x16x32_bf16 v[22:25], v[182:185], v[150:153], 0
	v_mfma_f32_16x16x32_bf16 v[26:29], v[186:189], v[150:153], 0
	v_mfma_f32_16x16x32_bf16 v[18:21], v[206:209], v[150:153], 0
	v_mfma_f32_16x16x32_bf16 v[10:13], v[158:161], v[154:157], 0
	v_mfma_f32_16x16x32_bf16 v[2:5], v[182:185], v[154:157], 0
	v_mfma_f32_16x16x32_bf16 v[14:17], v[186:189], v[154:157], 0
	v_mfma_f32_16x16x32_bf16 v[6:9], v[206:209], v[154:157], 0
	s_waitcnt vmcnt(0) lgkmcnt(0)
	s_barrier
	s_movk_i32 s7, 7
.Lg9_loop:
	v_mfma_f32_16x16x32_bf16 v[90:93], v[74:77], v[58:61], v[90:93]
	s_add_u32 m0, s6, 0x8000
	ds_read_b128 v[142:145], v106
	ds_read_b128 v[158:161], v108 offset:16384
	v_mfma_f32_16x16x32_bf16 v[54:57], v[78:81], v[58:61], v[54:57]
	global_load_lds_dwordx4 v98, s[2:3]
	v_mfma_f32_16x16x32_bf16 v[86:89], v[82:85], v[58:61], v[86:89]
	s_add_u32 m0, s6, 0x9000
	ds_read_b128 v[182:185], v108 offset:18432
	ds_read_b128 v[186:189], v108 offset:20480
	v_mfma_f32_16x16x32_bf16 v[50:53], v[94:97], v[58:61], v[50:53]
	global_load_lds_dwordx4 v99, s[2:3]
	v_mfma_f32_16x16x32_bf16 v[46:49], v[74:77], v[62:65], v[46:49]
	s_add_u32 m0, s6, 0xa000
	ds_read_b128 v[206:209], v108 offset:22528
	ds_read_b128 v[146:149], v106 offset:2048
	v_mfma_f32_16x16x32_bf16 v[38:41], v[78:81], v[62:65], v[38:41]
	global_load_lds_dwordx4 v100, s[2:3]
	v_mfma_f32_16x16x32_bf16 v[42:45], v[82:85], v[62:65], v[42:45]
	s_add_u32 m0, s6, 0xb000
	ds_read_b128 v[150:153], v106 offset:4096
	ds_read_b128 v[154:157], v106 offset:6144
	v_mfma_f32_16x16x32_bf16 v[34:37], v[94:97], v[62:65], v[34:37]
	global_load_lds_dwordx4 v101, s[2:3]
	v_mfma_f32_16x16x32_bf16 v[30:33], v[74:77], v[66:69], v[30:33]
	s_add_u32 m0, s6, 0xc000
	v_mfma_f32_16x16x32_bf16 v[22:25], v[78:81], v[66:69], v[22:25]
	global_load_lds_dwordx4 v102, s[4:5]
	v_mfma_f32_16x16x32_bf16 v[26:29], v[82:85], v[66:69], v[26:29]
	s_add_u32 m0, s6, 0xd000
	v_mfma_f32_16x16x32_bf16 v[18:21], v[94:97], v[66:69], v[18:21]
	global_load_lds_dwordx4 v103, s[4:5]
	v_mfma_f32_16x16x32_bf16 v[10:13], v[74:77], v[70:73], v[10:13]
	s_add_u32 m0, s6, 0xe000
	v_mfma_f32_16x16x32_bf16 v[2:5], v[78:81], v[70:73], v[2:5]
	global_load_lds_dwordx4 v104, s[4:5]
	v_mfma_f32_16x16x32_bf16 v[14:17], v[82:85], v[70:73], v[14:17]
	s_add_u32 m0, s6, 0xf000
	v_mfma_f32_16x16x32_bf16 v[6:9], v[94:97], v[70:73], v[6:9]
	global_load_lds_dwordx4 v105, s[4:5]
	s_add_u32 s2, s2, 0x80
	s_addc_u32 s3, s3, 0
	s_add_u32 s4, s4, 0x80
	s_addc_u32 s5, s5, 0
	s_waitcnt lgkmcnt(0)
	v_mfma_f32_16x16x32_bf16 v[90:93], v[158:161], v[142:145], v[90:93]
	ds_read_b128 v[58:61], v107
	ds_read_b128 v[74:77], v109 offset:16384
	v_mfma_f32_16x16x32_bf16 v[54:57], v[182:185], v[142:145], v[54:57]
	v_mfma_f32_16x16x32_bf16 v[86:89], v[186:189], v[142:145], v[86:89]
	ds_read_b128 v[78:81], v109 offset:18432
	ds_read_b128 v[82:85], v109 offset:20480
	v_mfma_f32_16x16x32_bf16 v[50:53], v[206:209], v[142:145], v[50:53]
	v_mfma_f32_16x16x32_bf16 v[46:49], v[158:161], v[146:149], v[46:49]
	ds_read_b128 v[94:97], v109 offset:22528
	ds_read_b128 v[62:65], v107 offset:2048
	v_mfma_f32_16x16x32_bf16 v[38:41], v[182:185], v[146:149], v[38:41]
	v_mfma_f32_16x16x32_bf16 v[42:45], v[186:189], v[146:149], v[42:45]
	ds_read_b128 v[66:69], v107 offset:4096
	ds_read_b128 v[70:73], v107 offset:6144
	v_mfma_f32_16x16x32_bf16 v[34:37], v[206:209], v[146:149], v[34:37]
	v_mfma_f32_16x16x32_bf16 v[30:33], v[158:161], v[150:153], v[30:33]
	v_mfma_f32_16x16x32_bf16 v[22:25], v[182:185], v[150:153], v[22:25]
	v_mfma_f32_16x16x32_bf16 v[26:29], v[186:189], v[150:153], v[26:29]
	v_mfma_f32_16x16x32_bf16 v[18:21], v[206:209], v[150:153], v[18:21]
	v_mfma_f32_16x16x32_bf16 v[10:13], v[158:161], v[154:157], v[10:13]
	v_mfma_f32_16x16x32_bf16 v[2:5], v[182:185], v[154:157], v[2:5]
	v_mfma_f32_16x16x32_bf16 v[14:17], v[186:189], v[154:157], v[14:17]
	v_mfma_f32_16x16x32_bf16 v[6:9], v[206:209], v[154:157], v[6:9]
	s_waitcnt vmcnt(0) lgkmcnt(0)
	s_barrier
	v_mfma_f32_16x16x32_bf16 v[90:93], v[74:77], v[58:61], v[90:93]
	s_mov_b32 m0, s6
	ds_read_b128 v[142:145], v106 offset:32768
	ds_read_b128 v[158:161], v108 offset:49152
	v_mfma_f32_16x16x32_bf16 v[54:57], v[78:81], v[58:61], v[54:57]
	global_load_lds_dwordx4 v98, s[2:3]
	v_mfma_f32_16x16x32_bf16 v[86:89], v[82:85], v[58:61], v[86:89]
	s_add_u32 m0, s6, 0x1000
	ds_read_b128 v[182:185], v108 offset:51200
	ds_read_b128 v[186:189], v108 offset:53248
	v_mfma_f32_16x16x32_bf16 v[50:53], v[94:97], v[58:61], v[50:53]
	global_load_lds_dwordx4 v99, s[2:3]
	v_mfma_f32_16x16x32_bf16 v[46:49], v[74:77], v[62:65], v[46:49]
	s_add_u32 m0, s6, 0x2000
	ds_read_b128 v[206:209], v108 offset:55296
	ds_read_b128 v[146:149], v106 offset:34816
	v_mfma_f32_16x16x32_bf16 v[38:41], v[78:81], v[62:65], v[38:41]
	global_load_lds_dwordx4 v100, s[2:3]
	v_mfma_f32_16x16x32_bf16 v[42:45], v[82:85], v[62:65], v[42:45]
	s_add_u32 m0, s6, 0x3000
	ds_read_b128 v[150:153], v106 offset:36864
	ds_read_b128 v[154:157], v106 offset:38912
	v_mfma_f32_16x16x32_bf16 v[34:37], v[94:97], v[62:65], v[34:37]
	global_load_lds_dwordx4 v101, s[2:3]
	v_mfma_f32_16x16x32_bf16 v[30:33], v[74:77], v[66:69], v[30:33]
	s_add_u32 m0, s6, 0x4000
	v_mfma_f32_16x16x32_bf16 v[22:25], v[78:81], v[66:69], v[22:25]
	global_load_lds_dwordx4 v102, s[4:5]
	v_mfma_f32_16x16x32_bf16 v[26:29], v[82:85], v[66:69], v[26:29]
	s_add_u32 m0, s6, 0x5000
	v_mfma_f32_16x16x32_bf16 v[18:21], v[94:97], v[66:69], v[18:21]
	global_load_lds_dwordx4 v103, s[4:5]
	v_mfma_f32_16x16x32_bf16 v[10:13], v[74:77], v[70:73], v[10:13]
	s_add_u32 m0, s6, 0x6000
	v_mfma_f32_16x16x32_bf16 v[2:5], v[78:81], v[70:73], v[2:5]
	global_load_lds_dwordx4 v104, s[4:5]
	v_mfma_f32_16x16x32_bf16 v[14:17], v[82:85], v[70:73], v[14:17]
	s_add_u32 m0, s6, 0x7000
	v_mfma_f32_16x16x32_bf16 v[6:9], v[94:97], v[70:73], v[6:9]
	global_load_lds_dwordx4 v105, s[4:5]
	s_add_u32 s2, s2, 0x80
	s_addc_u32 s3, s3, 0
	s_add_u32 s4, s4, 0x80
	s_addc_u32 s5, s5, 0
	s_waitcnt lgkmcnt(0)
	v_mfma_f32_16x16x32_bf16 v[90:93], v[158:161], v[142:145], v[90:93]
	ds_read_b128 v[58:61], v107 offset:32768
	ds_read_b128 v[74:77], v109 offset:49152
	v_mfma_f32_16x16x32_bf16 v[54:57], v[182:185], v[142:145], v[54:57]
	v_mfma_f32_16x16x32_bf16 v[86:89], v[186:189], v[142:145], v[86:89]
	ds_read_b128 v[78:81], v109 offset:51200
	ds_read_b128 v[82:85], v109 offset:53248
	v_mfma_f32_16x16x32_bf16 v[50:53], v[206:209], v[142:145], v[50:53]
	v_mfma_f32_16x16x32_bf16 v[46:49], v[158:161], v[146:149], v[46:49]
	ds_read_b128 v[94:97], v109 offset:55296
	ds_read_b128 v[62:65], v107 offset:34816
	v_mfma_f32_16x16x32_bf16 v[38:41], v[182:185], v[146:149], v[38:41]
	v_mfma_f32_16x16x32_bf16 v[42:45], v[186:189], v[146:149], v[42:45]
	ds_read_b128 v[66:69], v107 offset:36864
	ds_read_b128 v[70:73], v107 offset:38912
	v_mfma_f32_16x16x32_bf16 v[34:37], v[206:209], v[146:149], v[34:37]
	v_mfma_f32_16x16x32_bf16 v[30:33], v[158:161], v[150:153], v[30:33]
	v_mfma_f32_16x16x32_bf16 v[22:25], v[182:185], v[150:153], v[22:25]
	v_mfma_f32_16x16x32_bf16 v[26:29], v[186:189], v[150:153], v[26:29]
	v_mfma_f32_16x16x32_bf16 v[18:21], v[206:209], v[150:153], v[18:21]
	v_mfma_f32_16x16x32_bf16 v[10:13], v[158:161], v[154:157], v[10:13]
	v_mfma_f32_16x16x32_bf16 v[2:5], v[182:185], v[154:157], v[2:5]
	v_mfma_f32_16x16x32_bf16 v[14:17], v[186:189], v[154:157], v[14:17]
	v_mfma_f32_16x16x32_bf16 v[6:9], v[206:209], v[154:157], v[6:9]
	s_add_i32 s7, s7, -1
	s_waitcnt vmcnt(0) lgkmcnt(0)
	s_barrier
	s_cmp_lg_u32 s7, 0
	s_cbranch_scc1 .Lg9_loop
	v_readfirstlane_b32 s9, v134
	v_readlane_b32 s16, v234, 21
	s_add_u32 s9, s9, s16
	s_cmpk_ge_u32 s9, 5632
	s_cbranch_scc1 .Lg9_nonext
	s_and_b32 s10, s9, 7
	s_cmpk_lt_u32 s9, 5120
	s_cbranch_scc0 .Lg9_rem
	s_lshr_b32 s11, s9, 3
	s_lshr_b32 s12, s11, 6
	s_and_b32 s13, s12, 1
	s_lshl_b32 s13, s13, 3
	s_and_b32 s16, s11, 7
	s_add_u32 s13, s13, s16
	s_lshl_b32 s16, s10, 4
	s_add_u32 s13, s13, s16
	s_lshr_b32 s14, s12, 1
	s_lshl_b32 s14, s14, 3
	s_bfe_u32 s16, s11, 0x30003
	s_add_u32 s14, s14, s16
	s_branch .Lg9_tc
.Lg9_rem:
	s_sub_u32 s11, s9, 5120
	s_lshr_b32 s11, s11, 3
	s_and_b32 s13, s11, 15
	s_lshl_b32 s16, s10, 4
	s_add_u32 s13, s13, s16
	s_lshr_b32 s14, s11, 4
	s_add_u32 s14, s14, 40
.Lg9_tc:
	s_lshr_b32 s15, s6, 10
	s_lshl_b32 s15, s15, 3
	s_lshl_b32 s16, s13, 7
	s_add_u32 s16, s16, s15
	s_mul_i32 s16, s16, 0x880
	s_add_u32 s2, s80, s16
	s_addc_u32 s3, s81, 0
	s_lshl_b32 s16, s14, 7
	s_add_u32 s16, s16, s15
	s_mul_i32 s16, s16, 0x880
	s_add_u32 s4, s56, s16
	s_addc_u32 s5, s57, 0
	s_mov_b32 s9, 1
	v_writelane_b32 v234, s9, 23
	v_mfma_f32_16x16x32_bf16 v[90:93], v[74:77], v[58:61], v[90:93]
	s_add_u32 m0, s6, 0x8000
	ds_read_b128 v[142:145], v106
	ds_read_b128 v[158:161], v108 offset:16384
	v_mfma_f32_16x16x32_bf16 v[54:57], v[78:81], v[58:61], v[54:57]
	global_load_lds_dwordx4 v98, s[2:3]
	v_mfma_f32_16x16x32_bf16 v[86:89], v[82:85], v[58:61], v[86:89]
	s_add_u32 m0, s6, 0x9000
	ds_read_b128 v[182:185], v108 offset:18432
	ds_read_b128 v[186:189], v108 offset:20480
	v_mfma_f32_16x16x32_bf16 v[50:53], v[94:97], v[58:61], v[50:53]
	global_load_lds_dwordx4 v99, s[2:3]
	v_mfma_f32_16x16x32_bf16 v[46:49], v[74:77], v[62:65], v[46:49]
	s_add_u32 m0, s6, 0xa000
	ds_read_b128 v[206:209], v108 offset:22528
	ds_read_b128 v[146:149], v106 offset:2048
	v_mfma_f32_16x16x32_bf16 v[38:41], v[78:81], v[62:65], v[38:41]
	global_load_lds_dwordx4 v100, s[2:3]
	v_mfma_f32_16x16x32_bf16 v[42:45], v[82:85], v[62:65], v[42:45]
	s_add_u32 m0, s6, 0xb000
	ds_read_b128 v[150:153], v106 offset:4096
	ds_read_b128 v[154:157], v106 offset:6144
	v_mfma_f32_16x16x32_bf16 v[34:37], v[94:97], v[62:65], v[34:37]
	global_load_lds_dwordx4 v101, s[2:3]
	v_mfma_f32_16x16x32_bf16 v[30:33], v[74:77], v[66:69], v[30:33]
	s_add_u32 m0, s6, 0xc000
	v_mfma_f32_16x16x32_bf16 v[22:25], v[78:81], v[66:69], v[22:25]
	global_load_lds_dwordx4 v102, s[4:5]
	v_mfma_f32_16x16x32_bf16 v[26:29], v[82:85], v[66:69], v[26:29]
	s_add_u32 m0, s6, 0xd000
	v_mfma_f32_16x16x32_bf16 v[18:21], v[94:97], v[66:69], v[18:21]
	global_load_lds_dwordx4 v103, s[4:5]
	v_mfma_f32_16x16x32_bf16 v[10:13], v[74:77], v[70:73], v[10:13]
	s_add_u32 m0, s6, 0xe000
	v_mfma_f32_16x16x32_bf16 v[2:5], v[78:81], v[70:73], v[2:5]
	global_load_lds_dwordx4 v104, s[4:5]
	v_mfma_f32_16x16x32_bf16 v[14:17], v[82:85], v[70:73], v[14:17]
	s_add_u32 m0, s6, 0xf000
	v_mfma_f32_16x16x32_bf16 v[6:9], v[94:97], v[70:73], v[6:9]
	global_load_lds_dwordx4 v105, s[4:5]
	s_add_u32 s2, s2, 0x80
	s_addc_u32 s3, s3, 0
	s_add_u32 s4, s4, 0x80
	s_addc_u32 s5, s5, 0
	s_branch .Lg9_lastb
.Lg9_nonext:
	v_mfma_f32_16x16x32_bf16 v[90:93], v[74:77], v[58:61], v[90:93]
	ds_read_b128 v[142:145], v106
	ds_read_b128 v[158:161], v108 offset:16384
	v_mfma_f32_16x16x32_bf16 v[54:57], v[78:81], v[58:61], v[54:57]
	v_mfma_f32_16x16x32_bf16 v[86:89], v[82:85], v[58:61], v[86:89]
	ds_read_b128 v[182:185], v108 offset:18432
	ds_read_b128 v[186:189], v108 offset:20480
	v_mfma_f32_16x16x32_bf16 v[50:53], v[94:97], v[58:61], v[50:53]
	v_mfma_f32_16x16x32_bf16 v[46:49], v[74:77], v[62:65], v[46:49]
	ds_read_b128 v[206:209], v108 offset:22528
	ds_read_b128 v[146:149], v106 offset:2048
	v_mfma_f32_16x16x32_bf16 v[38:41], v[78:81], v[62:65], v[38:41]
	v_mfma_f32_16x16x32_bf16 v[42:45], v[82:85], v[62:65], v[42:45]
	ds_read_b128 v[150:153], v106 offset:4096
	ds_read_b128 v[154:157], v106 offset:6144
	v_mfma_f32_16x16x32_bf16 v[34:37], v[94:97], v[62:65], v[34:37]
	v_mfma_f32_16x16x32_bf16 v[30:33], v[74:77], v[66:69], v[30:33]
	v_mfma_f32_16x16x32_bf16 v[22:25], v[78:81], v[66:69], v[22:25]
	v_mfma_f32_16x16x32_bf16 v[26:29], v[82:85], v[66:69], v[26:29]
	v_mfma_f32_16x16x32_bf16 v[18:21], v[94:97], v[66:69], v[18:21]
	v_mfma_f32_16x16x32_bf16 v[10:13], v[74:77], v[70:73], v[10:13]
	v_mfma_f32_16x16x32_bf16 v[2:5], v[78:81], v[70:73], v[2:5]
	v_mfma_f32_16x16x32_bf16 v[14:17], v[82:85], v[70:73], v[14:17]
	v_mfma_f32_16x16x32_bf16 v[6:9], v[94:97], v[70:73], v[6:9]
.Lg9_lastb:
	s_waitcnt lgkmcnt(0)
	v_mfma_f32_16x16x32_bf16 v[90:93], v[158:161], v[142:145], v[90:93]
	ds_read_b128 v[58:61], v107
	ds_read_b128 v[74:77], v109 offset:16384
	v_mfma_f32_16x16x32_bf16 v[54:57], v[182:185], v[142:145], v[54:57]
	v_mfma_f32_16x16x32_bf16 v[86:89], v[186:189], v[142:145], v[86:89]
	ds_read_b128 v[78:81], v109 offset:18432
	ds_read_b128 v[82:85], v109 offset:20480
	v_mfma_f32_16x16x32_bf16 v[50:53], v[206:209], v[142:145], v[50:53]
	v_mfma_f32_16x16x32_bf16 v[46:49], v[158:161], v[146:149], v[46:49]
	ds_read_b128 v[94:97], v109 offset:22528
	ds_read_b128 v[62:65], v107 offset:2048
	v_mfma_f32_16x16x32_bf16 v[38:41], v[182:185], v[146:149], v[38:41]
	v_mfma_f32_16x16x32_bf16 v[42:45], v[186:189], v[146:149], v[42:45]
	ds_read_b128 v[66:69], v107 offset:4096
	ds_read_b128 v[70:73], v107 offset:6144
	v_mfma_f32_16x16x32_bf16 v[34:37], v[206:209], v[146:149], v[34:37]
	v_mfma_f32_16x16x32_bf16 v[30:33], v[158:161], v[150:153], v[30:33]
	v_mfma_f32_16x16x32_bf16 v[22:25], v[182:185], v[150:153], v[22:25]
	v_mfma_f32_16x16x32_bf16 v[26:29], v[186:189], v[150:153], v[26:29]
	v_mfma_f32_16x16x32_bf16 v[18:21], v[206:209], v[150:153], v[18:21]
	v_mfma_f32_16x16x32_bf16 v[10:13], v[158:161], v[154:157], v[10:13]
	v_mfma_f32_16x16x32_bf16 v[2:5], v[182:185], v[154:157], v[2:5]
	v_mfma_f32_16x16x32_bf16 v[14:17], v[186:189], v[154:157], v[14:17]
	v_mfma_f32_16x16x32_bf16 v[6:9], v[206:209], v[154:157], v[6:9]
	s_waitcnt lgkmcnt(0)
	s_barrier
	v_mfma_f32_16x16x32_bf16 v[90:93], v[74:77], v[58:61], v[90:93]
	v_mfma_f32_16x16x32_bf16 v[54:57], v[78:81], v[58:61], v[54:57]
	v_mfma_f32_16x16x32_bf16 v[86:89], v[82:85], v[58:61], v[86:89]
	v_mfma_f32_16x16x32_bf16 v[50:53], v[94:97], v[58:61], v[50:53]
	v_mfma_f32_16x16x32_bf16 v[46:49], v[74:77], v[62:65], v[46:49]
	v_mfma_f32_16x16x32_bf16 v[38:41], v[78:81], v[62:65], v[38:41]
	v_mfma_f32_16x16x32_bf16 v[42:45], v[82:85], v[62:65], v[42:45]
	v_mfma_f32_16x16x32_bf16 v[34:37], v[94:97], v[62:65], v[34:37]
	v_mfma_f32_16x16x32_bf16 v[30:33], v[74:77], v[66:69], v[30:33]
	v_mfma_f32_16x16x32_bf16 v[22:25], v[78:81], v[66:69], v[22:25]
	v_mfma_f32_16x16x32_bf16 v[26:29], v[82:85], v[66:69], v[26:29]
	v_mfma_f32_16x16x32_bf16 v[18:21], v[94:97], v[66:69], v[18:21]
	v_mfma_f32_16x16x32_bf16 v[10:13], v[74:77], v[70:73], v[10:13]
	v_mfma_f32_16x16x32_bf16 v[2:5], v[78:81], v[70:73], v[2:5]
	v_mfma_f32_16x16x32_bf16 v[14:17], v[82:85], v[70:73], v[14:17]
	v_mfma_f32_16x16x32_bf16 v[6:9], v[94:97], v[70:73], v[6:9]
	s_nop 7
	s_nop 2
	s_mov_b32 s21, 0x33000
	s_branch .LBB0_58
